# merge-GEMM gated epilogue: each chunk stored right after its compute (constant counted vmcnt) instead of all 16 stores at the end
# speedup vs baseline: 1.0075x; 1.0075x over previous
; DI unsigned pk_bf16(float lo, float hi) { unsigned r; asm("v_cvt_pk_bf16_f32 %0, %1, %2" : "=v"(r) : "v"(lo), "v"(hi)); return r; }
; DI float lo_f(unsigned w) { return __uint_as_float(w << 16); }
; DI float hi_f(unsigned w) { return __uint_as_float(w & 0xffff0000u); }
; DI float sigmoidf_(float x) { return __builtin_amdgcn_rcpf(1.f + __expf(-x)); }
;     DI void operator()(const f32x4 (&acc)[2][2][4][2], const Unit& u, int wr, int wc, int fr, int fq, LAS unsigned char* lds) const {
;     ...
;             bf16_t* Gb = (bf16_t*)(ws + WS_P) + C_MG + (size_t)u.pm * BM * IN_DIM + u.pn * BM;
; #pragma unroll
;             for (int ai = 0; ai < 2; ++ai)
; #pragma unroll
;                 for (int m = 0; m < 4; ++m)
; #pragma unroll
;                     for (int bj = 0; bj < 2; ++bj) {
;                         bf16_t* gp = Gb + ((rl0 + ai * HALF + m * 16) * (unsigned)IN_DIM + cl0 + bj * HALF);
;                         const u32x4 gv = *(const u32x4*)gp;
;                         const f32x4 v0 = acc[ai][bj][m][0], v1 = acc[ai][bj][m][1];
;                         u32x4 o;
;                         o[0] = pk_bf16(v0[0] * sigmoidf_(lo_f(gv[0])), v0[1] * sigmoidf_(hi_f(gv[0]))); o[1] = pk_bf16(v0[2] * sigmoidf_(lo_f(gv[1])), v0[3] * sigmoidf_(hi_f(gv[1])));
;                         o[2] = pk_bf16(v1[0] * sigmoidf_(lo_f(gv[2])), v1[1] * sigmoidf_(hi_f(gv[2]))); o[3] = pk_bf16(v1[2] * sigmoidf_(lo_f(gv[3])), v1[3] * sigmoidf_(hi_f(gv[3])));
;                         *(u32x4*)gp = o; }
.LBB0_328:
	s_and_b64 vcc, exec, s[20:21]
	s_cbranch_vccz .LBB0_330
	s_mul_i32 s21, s10, 0x264000
	s_mul_hi_i32 s20, s10, 0x264000
	s_add_u32 s21, s18, s21
	s_addc_u32 s20, s19, s20
	s_ashr_i32 s49, s48, 31
	s_lshl_b64 s[18:19], s[48:49], 1
	s_add_u32 s18, s21, s18
	s_addc_u32 s19, s20, s19
	s_add_u32 s42, s18, 0xb0e2e40
	s_addc_u32 s43, s19, 0
	s_movk_i32 s18, 0x1320
	v_mad_u32_u24 v130, v187, s18, v146
	v_lshlrev_b32_e32 v130, 1, v130
	v_add_u32_e32 v131, 0x26400, v130
	v_add_u32_e32 v132, 0x4c800, v130
	v_add_u32_e32 v133, 0x72c00, v130
	v_add_u32_e32 v179, 0x132000, v130
	v_add_u32_e32 v180, 0x158400, v130
	v_add_u32_e32 v240, 0x17e800, v130
	v_add_u32_e32 v241, 0x1a4c00, v130
	global_load_dwordx4 v[148:151], v130, s[42:43]
	global_load_dwordx4 v[152:155], v130, s[42:43] offset:256
	global_load_dwordx4 v[156:159], v131, s[42:43]
	global_load_dwordx4 v[160:163], v131, s[42:43] offset:256
	global_load_dwordx4 v[164:167], v132, s[42:43]
	global_load_dwordx4 v[168:171], v132, s[42:43] offset:256
	global_load_dwordx4 v[172:175], v133, s[42:43]
	global_load_dwordx4 v[190:193], v133, s[42:43] offset:256
	global_load_dwordx4 v[194:197], v179, s[42:43]
	global_load_dwordx4 v[198:201], v179, s[42:43] offset:256
	global_load_dwordx4 v[202:205], v180, s[42:43]
	global_load_dwordx4 v[206:209], v180, s[42:43] offset:256
	global_load_dwordx4 v[210:213], v240, s[42:43]
	global_load_dwordx4 v[214:217], v240, s[42:43] offset:256
	global_load_dwordx4 v[218:221], v241, s[42:43]
	global_load_dwordx4 v[222:225], v241, s[42:43] offset:256
	s_mov_b32 s18, 0xbfb8aa3b
	s_mov_b32 s20, 1.0
	s_waitcnt lgkmcnt(0)
	s_waitcnt vmcnt(15)
	v_lshlrev_b32_e32 v226, 16, v148
	v_and_b32_e32 v227, 0xffff0000, v148
	v_lshlrev_b32_e32 v228, 16, v149
	v_and_b32_e32 v229, 0xffff0000, v149
	v_lshlrev_b32_e32 v230, 16, v150
	v_and_b32_e32 v231, 0xffff0000, v150
	v_lshlrev_b32_e32 v248, 16, v151
	v_and_b32_e32 v249, 0xffff0000, v151
	v_pk_mul_f32 v[226:227], v[226:227], s[18:19] op_sel_hi:[1,0]
	v_pk_mul_f32 v[228:229], v[228:229], s[18:19] op_sel_hi:[1,0]
	v_pk_mul_f32 v[230:231], v[230:231], s[18:19] op_sel_hi:[1,0]
	v_pk_mul_f32 v[248:249], v[248:249], s[18:19] op_sel_hi:[1,0]
	v_exp_f32_e32 v226, v226
	v_exp_f32_e32 v227, v227
	v_exp_f32_e32 v228, v228
	v_exp_f32_e32 v229, v229
	v_exp_f32_e32 v230, v230
	v_exp_f32_e32 v231, v231
	v_exp_f32_e32 v248, v248
	v_exp_f32_e32 v249, v249
	v_pk_add_f32 v[226:227], v[226:227], s[20:21] op_sel_hi:[1,0]
	v_pk_add_f32 v[228:229], v[228:229], s[20:21] op_sel_hi:[1,0]
	v_pk_add_f32 v[230:231], v[230:231], s[20:21] op_sel_hi:[1,0]
	v_pk_add_f32 v[248:249], v[248:249], s[20:21] op_sel_hi:[1,0]
	v_rcp_f32_e32 v226, v226
	v_rcp_f32_e32 v227, v227
	v_rcp_f32_e32 v228, v228
	v_rcp_f32_e32 v229, v229
	v_rcp_f32_e32 v230, v230
	v_rcp_f32_e32 v231, v231
	v_rcp_f32_e32 v248, v248
	v_rcp_f32_e32 v249, v249
	v_pk_mul_f32 v[226:227], v[226:227], v[126:127]
	v_pk_mul_f32 v[228:229], v[228:229], v[128:129]
	v_pk_mul_f32 v[230:231], v[230:231], v[122:123]
	v_pk_mul_f32 v[248:249], v[248:249], v[124:125]
	v_cvt_pk_bf16_f32 v148, v226, v227
	v_cvt_pk_bf16_f32 v149, v228, v229
	v_cvt_pk_bf16_f32 v150, v230, v231
	v_cvt_pk_bf16_f32 v151, v248, v249
	global_store_dwordx4 v130, v[148:151], s[42:43]
	s_waitcnt vmcnt(15)
	v_lshlrev_b32_e32 v226, 16, v152
	v_and_b32_e32 v227, 0xffff0000, v152
	v_lshlrev_b32_e32 v228, 16, v153
	v_and_b32_e32 v229, 0xffff0000, v153
	v_lshlrev_b32_e32 v230, 16, v154
	v_and_b32_e32 v231, 0xffff0000, v154
	v_lshlrev_b32_e32 v248, 16, v155
	v_and_b32_e32 v249, 0xffff0000, v155
	v_pk_mul_f32 v[226:227], v[226:227], s[18:19] op_sel_hi:[1,0]
	v_pk_mul_f32 v[228:229], v[228:229], s[18:19] op_sel_hi:[1,0]
	v_pk_mul_f32 v[230:231], v[230:231], s[18:19] op_sel_hi:[1,0]
	v_pk_mul_f32 v[248:249], v[248:249], s[18:19] op_sel_hi:[1,0]
	v_exp_f32_e32 v226, v226
	v_exp_f32_e32 v227, v227
	v_exp_f32_e32 v228, v228
	v_exp_f32_e32 v229, v229
	v_exp_f32_e32 v230, v230
	v_exp_f32_e32 v231, v231
	v_exp_f32_e32 v248, v248
	v_exp_f32_e32 v249, v249
	v_pk_add_f32 v[226:227], v[226:227], s[20:21] op_sel_hi:[1,0]
	v_pk_add_f32 v[228:229], v[228:229], s[20:21] op_sel_hi:[1,0]
	v_pk_add_f32 v[230:231], v[230:231], s[20:21] op_sel_hi:[1,0]
	v_pk_add_f32 v[248:249], v[248:249], s[20:21] op_sel_hi:[1,0]
	v_rcp_f32_e32 v226, v226
	v_rcp_f32_e32 v227, v227
	v_rcp_f32_e32 v228, v228
	v_rcp_f32_e32 v229, v229
	v_rcp_f32_e32 v230, v230
	v_rcp_f32_e32 v231, v231
	v_rcp_f32_e32 v248, v248
	v_rcp_f32_e32 v249, v249
	v_pk_mul_f32 v[226:227], v[226:227], v[110:111]
	v_pk_mul_f32 v[228:229], v[228:229], v[112:113]
	v_pk_mul_f32 v[230:231], v[230:231], v[102:103]
	v_pk_mul_f32 v[248:249], v[248:249], v[104:105]
	v_cvt_pk_bf16_f32 v152, v226, v227
	v_cvt_pk_bf16_f32 v153, v228, v229
	v_cvt_pk_bf16_f32 v154, v230, v231
	v_cvt_pk_bf16_f32 v155, v248, v249
	global_store_dwordx4 v130, v[152:155], s[42:43] offset:256
	s_waitcnt vmcnt(15)
; DI unsigned pk_bf16(float lo, float hi) { unsigned r; asm("v_cvt_pk_bf16_f32 %0, %1, %2" : "=v"(r) : "v"(lo), "v"(hi)); return r; }
; DI float lo_f(unsigned w) { return __uint_as_float(w << 16); }
; DI float hi_f(unsigned w) { return __uint_as_float(w & 0xffff0000u); }
; DI float sigmoidf_(float x) { return __builtin_amdgcn_rcpf(1.f + __expf(-x)); }
;     DI void operator()(const f32x4 (&acc)[2][2][4][2], const Unit& u, int wr, int wc, int fr, int fq, LAS unsigned char* lds) const {
;     ...
;             bf16_t* Gb = (bf16_t*)(ws + WS_P) + C_MG + (size_t)u.pm * BM * IN_DIM + u.pn * BM;
; #pragma unroll
;             for (int ai = 0; ai < 2; ++ai)
; #pragma unroll
;                 for (int m = 0; m < 4; ++m)
; #pragma unroll
;                     for (int bj = 0; bj < 2; ++bj) {
;                         bf16_t* gp = Gb + ((rl0 + ai * HALF + m * 16) * (unsigned)IN_DIM + cl0 + bj * HALF);
;                         const u32x4 gv = *(const u32x4*)gp;
;                         const f32x4 v0 = acc[ai][bj][m][0], v1 = acc[ai][bj][m][1];
;                         u32x4 o;
;                         o[0] = pk_bf16(v0[0] * sigmoidf_(lo_f(gv[0])), v0[1] * sigmoidf_(hi_f(gv[0]))); o[1] = pk_bf16(v0[2] * sigmoidf_(lo_f(gv[1])), v0[3] * sigmoidf_(hi_f(gv[1])));
;                         o[2] = pk_bf16(v1[0] * sigmoidf_(lo_f(gv[2])), v1[1] * sigmoidf_(hi_f(gv[2]))); o[3] = pk_bf16(v1[2] * sigmoidf_(lo_f(gv[3])), v1[3] * sigmoidf_(hi_f(gv[3])));
;                         *(u32x4*)gp = o; }
	v_lshlrev_b32_e32 v226, 16, v156
	v_and_b32_e32 v227, 0xffff0000, v156
	v_lshlrev_b32_e32 v228, 16, v157
	v_and_b32_e32 v229, 0xffff0000, v157
	v_lshlrev_b32_e32 v230, 16, v158
	v_and_b32_e32 v231, 0xffff0000, v158
	v_lshlrev_b32_e32 v248, 16, v159
	v_and_b32_e32 v249, 0xffff0000, v159
	v_pk_mul_f32 v[226:227], v[226:227], s[18:19] op_sel_hi:[1,0]
	v_pk_mul_f32 v[228:229], v[228:229], s[18:19] op_sel_hi:[1,0]
	v_pk_mul_f32 v[230:231], v[230:231], s[18:19] op_sel_hi:[1,0]
	v_pk_mul_f32 v[248:249], v[248:249], s[18:19] op_sel_hi:[1,0]
	v_exp_f32_e32 v226, v226
	v_exp_f32_e32 v227, v227
	v_exp_f32_e32 v228, v228
	v_exp_f32_e32 v229, v229
	v_exp_f32_e32 v230, v230
	v_exp_f32_e32 v231, v231
	v_exp_f32_e32 v248, v248
	v_exp_f32_e32 v249, v249
	v_pk_add_f32 v[226:227], v[226:227], s[20:21] op_sel_hi:[1,0]
	v_pk_add_f32 v[228:229], v[228:229], s[20:21] op_sel_hi:[1,0]
	v_pk_add_f32 v[230:231], v[230:231], s[20:21] op_sel_hi:[1,0]
	v_pk_add_f32 v[248:249], v[248:249], s[20:21] op_sel_hi:[1,0]
	v_rcp_f32_e32 v226, v226
	v_rcp_f32_e32 v227, v227
	v_rcp_f32_e32 v228, v228
	v_rcp_f32_e32 v229, v229
	v_rcp_f32_e32 v230, v230
	v_rcp_f32_e32 v231, v231
	v_rcp_f32_e32 v248, v248
	v_rcp_f32_e32 v249, v249
	v_pk_mul_f32 v[226:227], v[226:227], v[118:119]
	v_pk_mul_f32 v[228:229], v[228:229], v[120:121]
	v_pk_mul_f32 v[230:231], v[230:231], v[114:115]
	v_pk_mul_f32 v[248:249], v[248:249], v[116:117]
	v_cvt_pk_bf16_f32 v156, v226, v227
	v_cvt_pk_bf16_f32 v157, v228, v229
	v_cvt_pk_bf16_f32 v158, v230, v231
	v_cvt_pk_bf16_f32 v159, v248, v249
	global_store_dwordx4 v131, v[156:159], s[42:43]
	s_waitcnt vmcnt(15)
	v_lshlrev_b32_e32 v226, 16, v160
	v_and_b32_e32 v227, 0xffff0000, v160
	v_lshlrev_b32_e32 v228, 16, v161
	v_and_b32_e32 v229, 0xffff0000, v161
	v_lshlrev_b32_e32 v230, 16, v162
	v_and_b32_e32 v231, 0xffff0000, v162
	v_lshlrev_b32_e32 v248, 16, v163
	v_and_b32_e32 v249, 0xffff0000, v163
	v_pk_mul_f32 v[226:227], v[226:227], s[18:19] op_sel_hi:[1,0]
	v_pk_mul_f32 v[228:229], v[228:229], s[18:19] op_sel_hi:[1,0]
	v_pk_mul_f32 v[230:231], v[230:231], s[18:19] op_sel_hi:[1,0]
	v_pk_mul_f32 v[248:249], v[248:249], s[18:19] op_sel_hi:[1,0]
	v_exp_f32_e32 v226, v226
	v_exp_f32_e32 v227, v227
	v_exp_f32_e32 v228, v228
	v_exp_f32_e32 v229, v229
	v_exp_f32_e32 v230, v230
	v_exp_f32_e32 v231, v231
	v_exp_f32_e32 v248, v248
	v_exp_f32_e32 v249, v249
	v_pk_add_f32 v[226:227], v[226:227], s[20:21] op_sel_hi:[1,0]
	v_pk_add_f32 v[228:229], v[228:229], s[20:21] op_sel_hi:[1,0]
	v_pk_add_f32 v[230:231], v[230:231], s[20:21] op_sel_hi:[1,0]
	v_pk_add_f32 v[248:249], v[248:249], s[20:21] op_sel_hi:[1,0]
	v_rcp_f32_e32 v226, v226
	v_rcp_f32_e32 v227, v227
	v_rcp_f32_e32 v228, v228
	v_rcp_f32_e32 v229, v229
	v_rcp_f32_e32 v230, v230
	v_rcp_f32_e32 v231, v231
	v_rcp_f32_e32 v248, v248
	v_rcp_f32_e32 v249, v249
	v_pk_mul_f32 v[226:227], v[226:227], v[94:95]
	v_pk_mul_f32 v[228:229], v[228:229], v[96:97]
	v_pk_mul_f32 v[230:231], v[230:231], v[86:87]
	v_pk_mul_f32 v[248:249], v[248:249], v[88:89]
	v_cvt_pk_bf16_f32 v160, v226, v227
	v_cvt_pk_bf16_f32 v161, v228, v229
	v_cvt_pk_bf16_f32 v162, v230, v231
	v_cvt_pk_bf16_f32 v163, v248, v249
	global_store_dwordx4 v131, v[160:163], s[42:43] offset:256
	s_waitcnt vmcnt(15)
	v_lshlrev_b32_e32 v226, 16, v164
	v_and_b32_e32 v227, 0xffff0000, v164
	v_lshlrev_b32_e32 v228, 16, v165
	v_and_b32_e32 v229, 0xffff0000, v165
	v_lshlrev_b32_e32 v230, 16, v166
	v_and_b32_e32 v231, 0xffff0000, v166
	v_lshlrev_b32_e32 v248, 16, v167
	v_and_b32_e32 v249, 0xffff0000, v167
	v_pk_mul_f32 v[226:227], v[226:227], s[18:19] op_sel_hi:[1,0]
	v_pk_mul_f32 v[228:229], v[228:229], s[18:19] op_sel_hi:[1,0]
	v_pk_mul_f32 v[230:231], v[230:231], s[18:19] op_sel_hi:[1,0]
	v_pk_mul_f32 v[248:249], v[248:249], s[18:19] op_sel_hi:[1,0]
	v_exp_f32_e32 v226, v226
	v_exp_f32_e32 v227, v227
	v_exp_f32_e32 v228, v228
	v_exp_f32_e32 v229, v229
	v_exp_f32_e32 v230, v230
	v_exp_f32_e32 v231, v231
	v_exp_f32_e32 v248, v248
	v_exp_f32_e32 v249, v249
	v_pk_add_f32 v[226:227], v[226:227], s[20:21] op_sel_hi:[1,0]
	v_pk_add_f32 v[228:229], v[228:229], s[20:21] op_sel_hi:[1,0]
	v_pk_add_f32 v[230:231], v[230:231], s[20:21] op_sel_hi:[1,0]
	v_pk_add_f32 v[248:249], v[248:249], s[20:21] op_sel_hi:[1,0]
	v_rcp_f32_e32 v226, v226
	v_rcp_f32_e32 v227, v227
	v_rcp_f32_e32 v228, v228
	v_rcp_f32_e32 v229, v229
	v_rcp_f32_e32 v230, v230
	v_rcp_f32_e32 v231, v231
	v_rcp_f32_e32 v248, v248
	v_rcp_f32_e32 v249, v249
	v_pk_mul_f32 v[226:227], v[226:227], v[106:107]
	v_pk_mul_f32 v[228:229], v[228:229], v[108:109]
	v_pk_mul_f32 v[230:231], v[230:231], v[98:99]
	v_pk_mul_f32 v[248:249], v[248:249], v[100:101]
	v_cvt_pk_bf16_f32 v164, v226, v227
	v_cvt_pk_bf16_f32 v165, v228, v229
	v_cvt_pk_bf16_f32 v166, v230, v231
	v_cvt_pk_bf16_f32 v167, v248, v249
	global_store_dwordx4 v132, v[164:167], s[42:43]
	s_waitcnt vmcnt(15)
; DI unsigned pk_bf16(float lo, float hi) { unsigned r; asm("v_cvt_pk_bf16_f32 %0, %1, %2" : "=v"(r) : "v"(lo), "v"(hi)); return r; }
; DI float lo_f(unsigned w) { return __uint_as_float(w << 16); }
; DI float hi_f(unsigned w) { return __uint_as_float(w & 0xffff0000u); }
; DI float sigmoidf_(float x) { return __builtin_amdgcn_rcpf(1.f + __expf(-x)); }
;     DI void operator()(const f32x4 (&acc)[2][2][4][2], const Unit& u, int wr, int wc, int fr, int fq, LAS unsigned char* lds) const {
;     ...
;             bf16_t* Gb = (bf16_t*)(ws + WS_P) + C_MG + (size_t)u.pm * BM * IN_DIM + u.pn * BM;
; #pragma unroll
;             for (int ai = 0; ai < 2; ++ai)
; #pragma unroll
;                 for (int m = 0; m < 4; ++m)
; #pragma unroll
;                     for (int bj = 0; bj < 2; ++bj) {
;                         bf16_t* gp = Gb + ((rl0 + ai * HALF + m * 16) * (unsigned)IN_DIM + cl0 + bj * HALF);
;                         const u32x4 gv = *(const u32x4*)gp;
;                         const f32x4 v0 = acc[ai][bj][m][0], v1 = acc[ai][bj][m][1];
;                         u32x4 o;
;                         o[0] = pk_bf16(v0[0] * sigmoidf_(lo_f(gv[0])), v0[1] * sigmoidf_(hi_f(gv[0]))); o[1] = pk_bf16(v0[2] * sigmoidf_(lo_f(gv[1])), v0[3] * sigmoidf_(hi_f(gv[1])));
;                         o[2] = pk_bf16(v1[0] * sigmoidf_(lo_f(gv[2])), v1[1] * sigmoidf_(hi_f(gv[2]))); o[3] = pk_bf16(v1[2] * sigmoidf_(lo_f(gv[3])), v1[3] * sigmoidf_(hi_f(gv[3])));
;                         *(u32x4*)gp = o; }
	v_lshlrev_b32_e32 v226, 16, v168
	v_and_b32_e32 v227, 0xffff0000, v168
	v_lshlrev_b32_e32 v228, 16, v169
	v_and_b32_e32 v229, 0xffff0000, v169
	v_lshlrev_b32_e32 v230, 16, v170
	v_and_b32_e32 v231, 0xffff0000, v170
	v_lshlrev_b32_e32 v248, 16, v171
	v_and_b32_e32 v249, 0xffff0000, v171
	v_pk_mul_f32 v[226:227], v[226:227], s[18:19] op_sel_hi:[1,0]
	v_pk_mul_f32 v[228:229], v[228:229], s[18:19] op_sel_hi:[1,0]
	v_pk_mul_f32 v[230:231], v[230:231], s[18:19] op_sel_hi:[1,0]
	v_pk_mul_f32 v[248:249], v[248:249], s[18:19] op_sel_hi:[1,0]
	v_exp_f32_e32 v226, v226
	v_exp_f32_e32 v227, v227
	v_exp_f32_e32 v228, v228
	v_exp_f32_e32 v229, v229
	v_exp_f32_e32 v230, v230
	v_exp_f32_e32 v231, v231
	v_exp_f32_e32 v248, v248
	v_exp_f32_e32 v249, v249
	v_pk_add_f32 v[226:227], v[226:227], s[20:21] op_sel_hi:[1,0]
	v_pk_add_f32 v[228:229], v[228:229], s[20:21] op_sel_hi:[1,0]
	v_pk_add_f32 v[230:231], v[230:231], s[20:21] op_sel_hi:[1,0]
	v_pk_add_f32 v[248:249], v[248:249], s[20:21] op_sel_hi:[1,0]
	v_rcp_f32_e32 v226, v226
	v_rcp_f32_e32 v227, v227
	v_rcp_f32_e32 v228, v228
	v_rcp_f32_e32 v229, v229
	v_rcp_f32_e32 v230, v230
	v_rcp_f32_e32 v231, v231
	v_rcp_f32_e32 v248, v248
	v_rcp_f32_e32 v249, v249
	v_pk_mul_f32 v[226:227], v[226:227], v[78:79]
	v_pk_mul_f32 v[228:229], v[228:229], v[80:81]
	v_pk_mul_f32 v[230:231], v[230:231], v[74:75]
	v_pk_mul_f32 v[248:249], v[248:249], v[76:77]
	v_cvt_pk_bf16_f32 v168, v226, v227
	v_cvt_pk_bf16_f32 v169, v228, v229
	v_cvt_pk_bf16_f32 v170, v230, v231
	v_cvt_pk_bf16_f32 v171, v248, v249
	global_store_dwordx4 v132, v[168:171], s[42:43] offset:256
	s_waitcnt vmcnt(15)
	v_lshlrev_b32_e32 v226, 16, v172
	v_and_b32_e32 v227, 0xffff0000, v172
	v_lshlrev_b32_e32 v228, 16, v173
	v_and_b32_e32 v229, 0xffff0000, v173
	v_lshlrev_b32_e32 v230, 16, v174
	v_and_b32_e32 v231, 0xffff0000, v174
	v_lshlrev_b32_e32 v248, 16, v175
	v_and_b32_e32 v249, 0xffff0000, v175
	v_pk_mul_f32 v[226:227], v[226:227], s[18:19] op_sel_hi:[1,0]
	v_pk_mul_f32 v[228:229], v[228:229], s[18:19] op_sel_hi:[1,0]
	v_pk_mul_f32 v[230:231], v[230:231], s[18:19] op_sel_hi:[1,0]
	v_pk_mul_f32 v[248:249], v[248:249], s[18:19] op_sel_hi:[1,0]
	v_exp_f32_e32 v226, v226
	v_exp_f32_e32 v227, v227
	v_exp_f32_e32 v228, v228
	v_exp_f32_e32 v229, v229
	v_exp_f32_e32 v230, v230
	v_exp_f32_e32 v231, v231
	v_exp_f32_e32 v248, v248
	v_exp_f32_e32 v249, v249
	v_pk_add_f32 v[226:227], v[226:227], s[20:21] op_sel_hi:[1,0]
	v_pk_add_f32 v[228:229], v[228:229], s[20:21] op_sel_hi:[1,0]
	v_pk_add_f32 v[230:231], v[230:231], s[20:21] op_sel_hi:[1,0]
	v_pk_add_f32 v[248:249], v[248:249], s[20:21] op_sel_hi:[1,0]
	v_rcp_f32_e32 v226, v226
	v_rcp_f32_e32 v227, v227
	v_rcp_f32_e32 v228, v228
	v_rcp_f32_e32 v229, v229
	v_rcp_f32_e32 v230, v230
	v_rcp_f32_e32 v231, v231
	v_rcp_f32_e32 v248, v248
	v_rcp_f32_e32 v249, v249
	v_pk_mul_f32 v[226:227], v[226:227], v[90:91]
	v_pk_mul_f32 v[228:229], v[228:229], v[92:93]
	v_pk_mul_f32 v[230:231], v[230:231], v[82:83]
	v_pk_mul_f32 v[248:249], v[248:249], v[84:85]
	v_cvt_pk_bf16_f32 v172, v226, v227
	v_cvt_pk_bf16_f32 v173, v228, v229
	v_cvt_pk_bf16_f32 v174, v230, v231
	v_cvt_pk_bf16_f32 v175, v248, v249
	global_store_dwordx4 v133, v[172:175], s[42:43]
	s_waitcnt vmcnt(15)
	v_lshlrev_b32_e32 v226, 16, v190
	v_and_b32_e32 v227, 0xffff0000, v190
	v_lshlrev_b32_e32 v228, 16, v191
	v_and_b32_e32 v229, 0xffff0000, v191
	v_lshlrev_b32_e32 v230, 16, v192
	v_and_b32_e32 v231, 0xffff0000, v192
	v_lshlrev_b32_e32 v248, 16, v193
	v_and_b32_e32 v249, 0xffff0000, v193
	v_pk_mul_f32 v[226:227], v[226:227], s[18:19] op_sel_hi:[1,0]
	v_pk_mul_f32 v[228:229], v[228:229], s[18:19] op_sel_hi:[1,0]
	v_pk_mul_f32 v[230:231], v[230:231], s[18:19] op_sel_hi:[1,0]
	v_pk_mul_f32 v[248:249], v[248:249], s[18:19] op_sel_hi:[1,0]
	v_exp_f32_e32 v226, v226
	v_exp_f32_e32 v227, v227
	v_exp_f32_e32 v228, v228
	v_exp_f32_e32 v229, v229
	v_exp_f32_e32 v230, v230
	v_exp_f32_e32 v231, v231
	v_exp_f32_e32 v248, v248
	v_exp_f32_e32 v249, v249
	v_pk_add_f32 v[226:227], v[226:227], s[20:21] op_sel_hi:[1,0]
	v_pk_add_f32 v[228:229], v[228:229], s[20:21] op_sel_hi:[1,0]
	v_pk_add_f32 v[230:231], v[230:231], s[20:21] op_sel_hi:[1,0]
	v_pk_add_f32 v[248:249], v[248:249], s[20:21] op_sel_hi:[1,0]
	v_rcp_f32_e32 v226, v226
	v_rcp_f32_e32 v227, v227
	v_rcp_f32_e32 v228, v228
	v_rcp_f32_e32 v229, v229
	v_rcp_f32_e32 v230, v230
	v_rcp_f32_e32 v231, v231
	v_rcp_f32_e32 v248, v248
	v_rcp_f32_e32 v249, v249
	v_pk_mul_f32 v[226:227], v[226:227], v[70:71]
	v_pk_mul_f32 v[228:229], v[228:229], v[72:73]
	v_pk_mul_f32 v[230:231], v[230:231], v[66:67]
	v_pk_mul_f32 v[248:249], v[248:249], v[68:69]
	v_cvt_pk_bf16_f32 v190, v226, v227
	v_cvt_pk_bf16_f32 v191, v228, v229
	v_cvt_pk_bf16_f32 v192, v230, v231
	v_cvt_pk_bf16_f32 v193, v248, v249
	global_store_dwordx4 v133, v[190:193], s[42:43] offset:256
	s_waitcnt vmcnt(15)
; DI unsigned pk_bf16(float lo, float hi) { unsigned r; asm("v_cvt_pk_bf16_f32 %0, %1, %2" : "=v"(r) : "v"(lo), "v"(hi)); return r; }
; DI float lo_f(unsigned w) { return __uint_as_float(w << 16); }
; DI float hi_f(unsigned w) { return __uint_as_float(w & 0xffff0000u); }
; DI float sigmoidf_(float x) { return __builtin_amdgcn_rcpf(1.f + __expf(-x)); }
;     DI void operator()(const f32x4 (&acc)[2][2][4][2], const Unit& u, int wr, int wc, int fr, int fq, LAS unsigned char* lds) const {
;     ...
;             bf16_t* Gb = (bf16_t*)(ws + WS_P) + C_MG + (size_t)u.pm * BM * IN_DIM + u.pn * BM;
; #pragma unroll
;             for (int ai = 0; ai < 2; ++ai)
; #pragma unroll
;                 for (int m = 0; m < 4; ++m)
; #pragma unroll
;                     for (int bj = 0; bj < 2; ++bj) {
;                         bf16_t* gp = Gb + ((rl0 + ai * HALF + m * 16) * (unsigned)IN_DIM + cl0 + bj * HALF);
;                         const u32x4 gv = *(const u32x4*)gp;
;                         const f32x4 v0 = acc[ai][bj][m][0], v1 = acc[ai][bj][m][1];
;                         u32x4 o;
;                         o[0] = pk_bf16(v0[0] * sigmoidf_(lo_f(gv[0])), v0[1] * sigmoidf_(hi_f(gv[0]))); o[1] = pk_bf16(v0[2] * sigmoidf_(lo_f(gv[1])), v0[3] * sigmoidf_(hi_f(gv[1])));
;                         o[2] = pk_bf16(v1[0] * sigmoidf_(lo_f(gv[2])), v1[1] * sigmoidf_(hi_f(gv[2]))); o[3] = pk_bf16(v1[2] * sigmoidf_(lo_f(gv[3])), v1[3] * sigmoidf_(hi_f(gv[3])));
;                         *(u32x4*)gp = o; }
	v_lshlrev_b32_e32 v226, 16, v194
	v_and_b32_e32 v227, 0xffff0000, v194
	v_lshlrev_b32_e32 v228, 16, v195
	v_and_b32_e32 v229, 0xffff0000, v195
	v_lshlrev_b32_e32 v230, 16, v196
	v_and_b32_e32 v231, 0xffff0000, v196
	v_lshlrev_b32_e32 v248, 16, v197
	v_and_b32_e32 v249, 0xffff0000, v197
	v_pk_mul_f32 v[226:227], v[226:227], s[18:19] op_sel_hi:[1,0]
	v_pk_mul_f32 v[228:229], v[228:229], s[18:19] op_sel_hi:[1,0]
	v_pk_mul_f32 v[230:231], v[230:231], s[18:19] op_sel_hi:[1,0]
	v_pk_mul_f32 v[248:249], v[248:249], s[18:19] op_sel_hi:[1,0]
	v_exp_f32_e32 v226, v226
	v_exp_f32_e32 v227, v227
	v_exp_f32_e32 v228, v228
	v_exp_f32_e32 v229, v229
	v_exp_f32_e32 v230, v230
	v_exp_f32_e32 v231, v231
	v_exp_f32_e32 v248, v248
	v_exp_f32_e32 v249, v249
	v_pk_add_f32 v[226:227], v[226:227], s[20:21] op_sel_hi:[1,0]
	v_pk_add_f32 v[228:229], v[228:229], s[20:21] op_sel_hi:[1,0]
	v_pk_add_f32 v[230:231], v[230:231], s[20:21] op_sel_hi:[1,0]
	v_pk_add_f32 v[248:249], v[248:249], s[20:21] op_sel_hi:[1,0]
	v_rcp_f32_e32 v226, v226
	v_rcp_f32_e32 v227, v227
	v_rcp_f32_e32 v228, v228
	v_rcp_f32_e32 v229, v229
	v_rcp_f32_e32 v230, v230
	v_rcp_f32_e32 v231, v231
	v_rcp_f32_e32 v248, v248
	v_rcp_f32_e32 v249, v249
	v_pk_mul_f32 v[226:227], v[226:227], v[62:63]
	v_pk_mul_f32 v[228:229], v[228:229], v[64:65]
	v_pk_mul_f32 v[230:231], v[230:231], v[58:59]
	v_pk_mul_f32 v[248:249], v[248:249], v[60:61]
	v_cvt_pk_bf16_f32 v194, v226, v227
	v_cvt_pk_bf16_f32 v195, v228, v229
	v_cvt_pk_bf16_f32 v196, v230, v231
	v_cvt_pk_bf16_f32 v197, v248, v249
	global_store_dwordx4 v179, v[194:197], s[42:43]
	s_waitcnt vmcnt(15)
	v_lshlrev_b32_e32 v226, 16, v198
	v_and_b32_e32 v227, 0xffff0000, v198
	v_lshlrev_b32_e32 v228, 16, v199
	v_and_b32_e32 v229, 0xffff0000, v199
	v_lshlrev_b32_e32 v230, 16, v200
	v_and_b32_e32 v231, 0xffff0000, v200
	v_lshlrev_b32_e32 v248, 16, v201
	v_and_b32_e32 v249, 0xffff0000, v201
	v_pk_mul_f32 v[226:227], v[226:227], s[18:19] op_sel_hi:[1,0]
	v_pk_mul_f32 v[228:229], v[228:229], s[18:19] op_sel_hi:[1,0]
	v_pk_mul_f32 v[230:231], v[230:231], s[18:19] op_sel_hi:[1,0]
	v_pk_mul_f32 v[248:249], v[248:249], s[18:19] op_sel_hi:[1,0]
	v_exp_f32_e32 v226, v226
	v_exp_f32_e32 v227, v227
	v_exp_f32_e32 v228, v228
	v_exp_f32_e32 v229, v229
	v_exp_f32_e32 v230, v230
	v_exp_f32_e32 v231, v231
	v_exp_f32_e32 v248, v248
	v_exp_f32_e32 v249, v249
	v_pk_add_f32 v[226:227], v[226:227], s[20:21] op_sel_hi:[1,0]
	v_pk_add_f32 v[228:229], v[228:229], s[20:21] op_sel_hi:[1,0]
	v_pk_add_f32 v[230:231], v[230:231], s[20:21] op_sel_hi:[1,0]
	v_pk_add_f32 v[248:249], v[248:249], s[20:21] op_sel_hi:[1,0]
	v_rcp_f32_e32 v226, v226
	v_rcp_f32_e32 v227, v227
	v_rcp_f32_e32 v228, v228
	v_rcp_f32_e32 v229, v229
	v_rcp_f32_e32 v230, v230
	v_rcp_f32_e32 v231, v231
	v_rcp_f32_e32 v248, v248
	v_rcp_f32_e32 v249, v249
	v_pk_mul_f32 v[226:227], v[226:227], v[42:43]
	v_pk_mul_f32 v[228:229], v[228:229], v[44:45]
	v_pk_mul_f32 v[230:231], v[230:231], v[34:35]
	v_pk_mul_f32 v[248:249], v[248:249], v[36:37]
	v_cvt_pk_bf16_f32 v198, v226, v227
	v_cvt_pk_bf16_f32 v199, v228, v229
	v_cvt_pk_bf16_f32 v200, v230, v231
	v_cvt_pk_bf16_f32 v201, v248, v249
	global_store_dwordx4 v179, v[198:201], s[42:43] offset:256
	s_waitcnt vmcnt(15)
	v_lshlrev_b32_e32 v226, 16, v202
	v_and_b32_e32 v227, 0xffff0000, v202
	v_lshlrev_b32_e32 v228, 16, v203
	v_and_b32_e32 v229, 0xffff0000, v203
	v_lshlrev_b32_e32 v230, 16, v204
	v_and_b32_e32 v231, 0xffff0000, v204
	v_lshlrev_b32_e32 v248, 16, v205
	v_and_b32_e32 v249, 0xffff0000, v205
	v_pk_mul_f32 v[226:227], v[226:227], s[18:19] op_sel_hi:[1,0]
	v_pk_mul_f32 v[228:229], v[228:229], s[18:19] op_sel_hi:[1,0]
	v_pk_mul_f32 v[230:231], v[230:231], s[18:19] op_sel_hi:[1,0]
	v_pk_mul_f32 v[248:249], v[248:249], s[18:19] op_sel_hi:[1,0]
	v_exp_f32_e32 v226, v226
	v_exp_f32_e32 v227, v227
	v_exp_f32_e32 v228, v228
	v_exp_f32_e32 v229, v229
	v_exp_f32_e32 v230, v230
	v_exp_f32_e32 v231, v231
	v_exp_f32_e32 v248, v248
	v_exp_f32_e32 v249, v249
	v_pk_add_f32 v[226:227], v[226:227], s[20:21] op_sel_hi:[1,0]
	v_pk_add_f32 v[228:229], v[228:229], s[20:21] op_sel_hi:[1,0]
	v_pk_add_f32 v[230:231], v[230:231], s[20:21] op_sel_hi:[1,0]
	v_pk_add_f32 v[248:249], v[248:249], s[20:21] op_sel_hi:[1,0]
	v_rcp_f32_e32 v226, v226
	v_rcp_f32_e32 v227, v227
	v_rcp_f32_e32 v228, v228
	v_rcp_f32_e32 v229, v229
	v_rcp_f32_e32 v230, v230
	v_rcp_f32_e32 v231, v231
	v_rcp_f32_e32 v248, v248
	v_rcp_f32_e32 v249, v249
	v_pk_mul_f32 v[226:227], v[226:227], v[54:55]
	v_pk_mul_f32 v[228:229], v[228:229], v[56:57]
	v_pk_mul_f32 v[230:231], v[230:231], v[50:51]
	v_pk_mul_f32 v[248:249], v[248:249], v[52:53]
	v_cvt_pk_bf16_f32 v202, v226, v227
	v_cvt_pk_bf16_f32 v203, v228, v229
	v_cvt_pk_bf16_f32 v204, v230, v231
	v_cvt_pk_bf16_f32 v205, v248, v249
	global_store_dwordx4 v180, v[202:205], s[42:43]
	s_waitcnt vmcnt(15)
; DI unsigned pk_bf16(float lo, float hi) { unsigned r; asm("v_cvt_pk_bf16_f32 %0, %1, %2" : "=v"(r) : "v"(lo), "v"(hi)); return r; }
; DI float lo_f(unsigned w) { return __uint_as_float(w << 16); }
; DI float hi_f(unsigned w) { return __uint_as_float(w & 0xffff0000u); }
; DI float sigmoidf_(float x) { return __builtin_amdgcn_rcpf(1.f + __expf(-x)); }
;     DI void operator()(const f32x4 (&acc)[2][2][4][2], const Unit& u, int wr, int wc, int fr, int fq, LAS unsigned char* lds) const {
;     ...
;             bf16_t* Gb = (bf16_t*)(ws + WS_P) + C_MG + (size_t)u.pm * BM * IN_DIM + u.pn * BM;
; #pragma unroll
;             for (int ai = 0; ai < 2; ++ai)
; #pragma unroll
;                 for (int m = 0; m < 4; ++m)
; #pragma unroll
;                     for (int bj = 0; bj < 2; ++bj) {
;                         bf16_t* gp = Gb + ((rl0 + ai * HALF + m * 16) * (unsigned)IN_DIM + cl0 + bj * HALF);
;                         const u32x4 gv = *(const u32x4*)gp;
;                         const f32x4 v0 = acc[ai][bj][m][0], v1 = acc[ai][bj][m][1];
;                         u32x4 o;
;                         o[0] = pk_bf16(v0[0] * sigmoidf_(lo_f(gv[0])), v0[1] * sigmoidf_(hi_f(gv[0]))); o[1] = pk_bf16(v0[2] * sigmoidf_(lo_f(gv[1])), v0[3] * sigmoidf_(hi_f(gv[1])));
;                         o[2] = pk_bf16(v1[0] * sigmoidf_(lo_f(gv[2])), v1[1] * sigmoidf_(hi_f(gv[2]))); o[3] = pk_bf16(v1[2] * sigmoidf_(lo_f(gv[3])), v1[3] * sigmoidf_(hi_f(gv[3])));
;                         *(u32x4*)gp = o; }
	v_lshlrev_b32_e32 v226, 16, v206
	v_and_b32_e32 v227, 0xffff0000, v206
	v_lshlrev_b32_e32 v228, 16, v207
	v_and_b32_e32 v229, 0xffff0000, v207
	v_lshlrev_b32_e32 v230, 16, v208
	v_and_b32_e32 v231, 0xffff0000, v208
	v_lshlrev_b32_e32 v248, 16, v209
	v_and_b32_e32 v249, 0xffff0000, v209
	v_pk_mul_f32 v[226:227], v[226:227], s[18:19] op_sel_hi:[1,0]
	v_pk_mul_f32 v[228:229], v[228:229], s[18:19] op_sel_hi:[1,0]
	v_pk_mul_f32 v[230:231], v[230:231], s[18:19] op_sel_hi:[1,0]
	v_pk_mul_f32 v[248:249], v[248:249], s[18:19] op_sel_hi:[1,0]
	v_exp_f32_e32 v226, v226
	v_exp_f32_e32 v227, v227
	v_exp_f32_e32 v228, v228
	v_exp_f32_e32 v229, v229
	v_exp_f32_e32 v230, v230
	v_exp_f32_e32 v231, v231
	v_exp_f32_e32 v248, v248
	v_exp_f32_e32 v249, v249
	v_pk_add_f32 v[226:227], v[226:227], s[20:21] op_sel_hi:[1,0]
	v_pk_add_f32 v[228:229], v[228:229], s[20:21] op_sel_hi:[1,0]
	v_pk_add_f32 v[230:231], v[230:231], s[20:21] op_sel_hi:[1,0]
	v_pk_add_f32 v[248:249], v[248:249], s[20:21] op_sel_hi:[1,0]
	v_rcp_f32_e32 v226, v226
	v_rcp_f32_e32 v227, v227
	v_rcp_f32_e32 v228, v228
	v_rcp_f32_e32 v229, v229
	v_rcp_f32_e32 v230, v230
	v_rcp_f32_e32 v231, v231
	v_rcp_f32_e32 v248, v248
	v_rcp_f32_e32 v249, v249
	v_pk_mul_f32 v[226:227], v[226:227], v[26:27]
	v_pk_mul_f32 v[228:229], v[228:229], v[28:29]
	v_pk_mul_f32 v[230:231], v[230:231], v[18:19]
	v_pk_mul_f32 v[248:249], v[248:249], v[20:21]
	v_cvt_pk_bf16_f32 v206, v226, v227
	v_cvt_pk_bf16_f32 v207, v228, v229
	v_cvt_pk_bf16_f32 v208, v230, v231
	v_cvt_pk_bf16_f32 v209, v248, v249
	global_store_dwordx4 v180, v[206:209], s[42:43] offset:256
	s_waitcnt vmcnt(15)
	v_lshlrev_b32_e32 v226, 16, v210
	v_and_b32_e32 v227, 0xffff0000, v210
	v_lshlrev_b32_e32 v228, 16, v211
	v_and_b32_e32 v229, 0xffff0000, v211
	v_lshlrev_b32_e32 v230, 16, v212
	v_and_b32_e32 v231, 0xffff0000, v212
	v_lshlrev_b32_e32 v248, 16, v213
	v_and_b32_e32 v249, 0xffff0000, v213
	v_pk_mul_f32 v[226:227], v[226:227], s[18:19] op_sel_hi:[1,0]
	v_pk_mul_f32 v[228:229], v[228:229], s[18:19] op_sel_hi:[1,0]
	v_pk_mul_f32 v[230:231], v[230:231], s[18:19] op_sel_hi:[1,0]
	v_pk_mul_f32 v[248:249], v[248:249], s[18:19] op_sel_hi:[1,0]
	v_exp_f32_e32 v226, v226
	v_exp_f32_e32 v227, v227
	v_exp_f32_e32 v228, v228
	v_exp_f32_e32 v229, v229
	v_exp_f32_e32 v230, v230
	v_exp_f32_e32 v231, v231
	v_exp_f32_e32 v248, v248
	v_exp_f32_e32 v249, v249
	v_pk_add_f32 v[226:227], v[226:227], s[20:21] op_sel_hi:[1,0]
	v_pk_add_f32 v[228:229], v[228:229], s[20:21] op_sel_hi:[1,0]
	v_pk_add_f32 v[230:231], v[230:231], s[20:21] op_sel_hi:[1,0]
	v_pk_add_f32 v[248:249], v[248:249], s[20:21] op_sel_hi:[1,0]
	v_rcp_f32_e32 v226, v226
	v_rcp_f32_e32 v227, v227
	v_rcp_f32_e32 v228, v228
	v_rcp_f32_e32 v229, v229
	v_rcp_f32_e32 v230, v230
	v_rcp_f32_e32 v231, v231
	v_rcp_f32_e32 v248, v248
	v_rcp_f32_e32 v249, v249
	v_pk_mul_f32 v[226:227], v[226:227], v[46:47]
	v_pk_mul_f32 v[228:229], v[228:229], v[48:49]
	v_pk_mul_f32 v[230:231], v[230:231], v[38:39]
	v_pk_mul_f32 v[248:249], v[248:249], v[40:41]
	v_cvt_pk_bf16_f32 v210, v226, v227
	v_cvt_pk_bf16_f32 v211, v228, v229
	v_cvt_pk_bf16_f32 v212, v230, v231
	v_cvt_pk_bf16_f32 v213, v248, v249
	global_store_dwordx4 v240, v[210:213], s[42:43]
	s_waitcnt vmcnt(15)
; DI unsigned pk_bf16(float lo, float hi) { unsigned r; asm("v_cvt_pk_bf16_f32 %0, %1, %2" : "=v"(r) : "v"(lo), "v"(hi)); return r; }
; DI float lo_f(unsigned w) { return __uint_as_float(w << 16); }
; DI float hi_f(unsigned w) { return __uint_as_float(w & 0xffff0000u); }
; DI float sigmoidf_(float x) { return __builtin_amdgcn_rcpf(1.f + __expf(-x)); }
;     DI void operator()(const f32x4 (&acc)[2][2][4][2], const Unit& u, int wr, int wc, int fr, int fq, LAS unsigned char* lds) const {
;     ...
;             bf16_t* Gb = (bf16_t*)(ws + WS_P) + C_MG + (size_t)u.pm * BM * IN_DIM + u.pn * BM;
; #pragma unroll
;             for (int ai = 0; ai < 2; ++ai)
; #pragma unroll
;                 for (int m = 0; m < 4; ++m)
; #pragma unroll
;                     for (int bj = 0; bj < 2; ++bj) {
;                         bf16_t* gp = Gb + ((rl0 + ai * HALF + m * 16) * (unsigned)IN_DIM + cl0 + bj * HALF);
;                         const u32x4 gv = *(const u32x4*)gp;
;                         const f32x4 v0 = acc[ai][bj][m][0], v1 = acc[ai][bj][m][1];
;                         u32x4 o;
;                         o[0] = pk_bf16(v0[0] * sigmoidf_(lo_f(gv[0])), v0[1] * sigmoidf_(hi_f(gv[0]))); o[1] = pk_bf16(v0[2] * sigmoidf_(lo_f(gv[1])), v0[3] * sigmoidf_(hi_f(gv[1])));
;                         o[2] = pk_bf16(v1[0] * sigmoidf_(lo_f(gv[2])), v1[1] * sigmoidf_(hi_f(gv[2]))); o[3] = pk_bf16(v1[2] * sigmoidf_(lo_f(gv[3])), v1[3] * sigmoidf_(hi_f(gv[3])));
;                         *(u32x4*)gp = o; }
	v_lshlrev_b32_e32 v226, 16, v214
	v_and_b32_e32 v227, 0xffff0000, v214
	v_lshlrev_b32_e32 v228, 16, v215
	v_and_b32_e32 v229, 0xffff0000, v215
	v_lshlrev_b32_e32 v230, 16, v216
	v_and_b32_e32 v231, 0xffff0000, v216
	v_lshlrev_b32_e32 v248, 16, v217
	v_and_b32_e32 v249, 0xffff0000, v217
	v_pk_mul_f32 v[226:227], v[226:227], s[18:19] op_sel_hi:[1,0]
	v_pk_mul_f32 v[228:229], v[228:229], s[18:19] op_sel_hi:[1,0]
	v_pk_mul_f32 v[230:231], v[230:231], s[18:19] op_sel_hi:[1,0]
	v_pk_mul_f32 v[248:249], v[248:249], s[18:19] op_sel_hi:[1,0]
	v_exp_f32_e32 v226, v226
	v_exp_f32_e32 v227, v227
	v_exp_f32_e32 v228, v228
	v_exp_f32_e32 v229, v229
	v_exp_f32_e32 v230, v230
	v_exp_f32_e32 v231, v231
	v_exp_f32_e32 v248, v248
	v_exp_f32_e32 v249, v249
	v_pk_add_f32 v[226:227], v[226:227], s[20:21] op_sel_hi:[1,0]
	v_pk_add_f32 v[228:229], v[228:229], s[20:21] op_sel_hi:[1,0]
	v_pk_add_f32 v[230:231], v[230:231], s[20:21] op_sel_hi:[1,0]
	v_pk_add_f32 v[248:249], v[248:249], s[20:21] op_sel_hi:[1,0]
	v_rcp_f32_e32 v226, v226
	v_rcp_f32_e32 v227, v227
	v_rcp_f32_e32 v228, v228
	v_rcp_f32_e32 v229, v229
	v_rcp_f32_e32 v230, v230
	v_rcp_f32_e32 v231, v231
	v_rcp_f32_e32 v248, v248
	v_rcp_f32_e32 v249, v249
	v_pk_mul_f32 v[226:227], v[226:227], v[14:15]
	v_pk_mul_f32 v[228:229], v[228:229], v[16:17]
	v_pk_mul_f32 v[230:231], v[230:231], v[10:11]
	v_pk_mul_f32 v[248:249], v[248:249], v[12:13]
	v_cvt_pk_bf16_f32 v214, v226, v227
	v_cvt_pk_bf16_f32 v215, v228, v229
	v_cvt_pk_bf16_f32 v216, v230, v231
	v_cvt_pk_bf16_f32 v217, v248, v249
	global_store_dwordx4 v240, v[214:217], s[42:43] offset:256
	s_waitcnt vmcnt(15)
	v_lshlrev_b32_e32 v226, 16, v218
	v_and_b32_e32 v227, 0xffff0000, v218
	v_lshlrev_b32_e32 v228, 16, v219
	v_and_b32_e32 v229, 0xffff0000, v219
	v_lshlrev_b32_e32 v230, 16, v220
	v_and_b32_e32 v231, 0xffff0000, v220
	v_lshlrev_b32_e32 v248, 16, v221
	v_and_b32_e32 v249, 0xffff0000, v221
	v_pk_mul_f32 v[226:227], v[226:227], s[18:19] op_sel_hi:[1,0]
	v_pk_mul_f32 v[228:229], v[228:229], s[18:19] op_sel_hi:[1,0]
	v_pk_mul_f32 v[230:231], v[230:231], s[18:19] op_sel_hi:[1,0]
	v_pk_mul_f32 v[248:249], v[248:249], s[18:19] op_sel_hi:[1,0]
	v_exp_f32_e32 v226, v226
	v_exp_f32_e32 v227, v227
	v_exp_f32_e32 v228, v228
	v_exp_f32_e32 v229, v229
	v_exp_f32_e32 v230, v230
	v_exp_f32_e32 v231, v231
	v_exp_f32_e32 v248, v248
	v_exp_f32_e32 v249, v249
	v_pk_add_f32 v[226:227], v[226:227], s[20:21] op_sel_hi:[1,0]
	v_pk_add_f32 v[228:229], v[228:229], s[20:21] op_sel_hi:[1,0]
	v_pk_add_f32 v[230:231], v[230:231], s[20:21] op_sel_hi:[1,0]
	v_pk_add_f32 v[248:249], v[248:249], s[20:21] op_sel_hi:[1,0]
	v_rcp_f32_e32 v226, v226
	v_rcp_f32_e32 v227, v227
	v_rcp_f32_e32 v228, v228
	v_rcp_f32_e32 v229, v229
	v_rcp_f32_e32 v230, v230
	v_rcp_f32_e32 v231, v231
	v_rcp_f32_e32 v248, v248
	v_rcp_f32_e32 v249, v249
	v_pk_mul_f32 v[226:227], v[226:227], v[30:31]
	v_pk_mul_f32 v[228:229], v[228:229], v[32:33]
	v_pk_mul_f32 v[230:231], v[230:231], v[22:23]
	v_pk_mul_f32 v[248:249], v[248:249], v[24:25]
	v_cvt_pk_bf16_f32 v218, v226, v227
	v_cvt_pk_bf16_f32 v219, v228, v229
	v_cvt_pk_bf16_f32 v220, v230, v231
	v_cvt_pk_bf16_f32 v221, v248, v249
	global_store_dwordx4 v241, v[218:221], s[42:43]
	s_waitcnt vmcnt(15)
	v_lshlrev_b32_e32 v226, 16, v222
	v_and_b32_e32 v227, 0xffff0000, v222
	v_lshlrev_b32_e32 v228, 16, v223
	v_and_b32_e32 v229, 0xffff0000, v223
	v_lshlrev_b32_e32 v230, 16, v224
	v_and_b32_e32 v231, 0xffff0000, v224
	v_lshlrev_b32_e32 v248, 16, v225
	v_and_b32_e32 v249, 0xffff0000, v225
	v_pk_mul_f32 v[226:227], v[226:227], s[18:19] op_sel_hi:[1,0]
	v_pk_mul_f32 v[228:229], v[228:229], s[18:19] op_sel_hi:[1,0]
	v_pk_mul_f32 v[230:231], v[230:231], s[18:19] op_sel_hi:[1,0]
	v_pk_mul_f32 v[248:249], v[248:249], s[18:19] op_sel_hi:[1,0]
	v_exp_f32_e32 v226, v226
	v_exp_f32_e32 v227, v227
	v_exp_f32_e32 v228, v228
	v_exp_f32_e32 v229, v229
	v_exp_f32_e32 v230, v230
	v_exp_f32_e32 v231, v231
	v_exp_f32_e32 v248, v248
	v_exp_f32_e32 v249, v249
	v_pk_add_f32 v[226:227], v[226:227], s[20:21] op_sel_hi:[1,0]
	v_pk_add_f32 v[228:229], v[228:229], s[20:21] op_sel_hi:[1,0]
	v_pk_add_f32 v[230:231], v[230:231], s[20:21] op_sel_hi:[1,0]
	v_pk_add_f32 v[248:249], v[248:249], s[20:21] op_sel_hi:[1,0]
	v_rcp_f32_e32 v226, v226
	v_rcp_f32_e32 v227, v227
	v_rcp_f32_e32 v228, v228
	v_rcp_f32_e32 v229, v229
	v_rcp_f32_e32 v230, v230
	v_rcp_f32_e32 v231, v231
	v_rcp_f32_e32 v248, v248
	v_rcp_f32_e32 v249, v249
	v_pk_mul_f32 v[226:227], v[226:227], v[6:7]
	v_pk_mul_f32 v[228:229], v[228:229], v[8:9]
	v_pk_mul_f32 v[230:231], v[230:231], v[2:3]
	v_pk_mul_f32 v[248:249], v[248:249], v[4:5]
	v_cvt_pk_bf16_f32 v222, v226, v227
	v_cvt_pk_bf16_f32 v223, v228, v229
	v_cvt_pk_bf16_f32 v224, v230, v231
	v_cvt_pk_bf16_f32 v225, v248, v249
	global_store_dwordx4 v241, v[222:225], s[42:43] offset:256
